# in-proj GEMM K-loop: barrier moved one MFMA pair earlier (two pairs issue after it), next half-step first fragments fetched under four MFMAs
# speedup vs baseline: 1.0651x; 1.0016x over previous
; #define G_LOAD(AG, BG, kt, RA, RB) do { const int k0_ = (kt) * 64; int ac_ = k0_; if (g.remap) ac_ = k0_ < 512 ? k0_ : (k0_ < 1024 ? g.seg2 + k0_ - 512 : 2304 + k0_ - 1024); \
;     _Pragma("unroll") for (int i = 0; i < 4; ++i) { RA[i] = *(const u32x4*)(AG + (size_t)(64 * i) * g.lda + ac_); RB[i] = *(const u32x4*)(BG + (size_t)(64 * i) * g.K + k0_); } } while (0)
; #define G_WRITE(buf, RA, RB) do { _Pragma("unroll") for (int i = 0; i < 4; ++i) { *(u32x4*)(lds + (buf) * 65536 + i * 8192 + soff) = RA[i]; *(u32x4*)(lds + (buf) * 65536 + 32768 + i * 8192 + soff) = RB[i]; } } while (0)
; template <int EPI>
; DI void gemm_phase(char* lds, const Params& p, const GemmDesc g, int layer) {
;     ...
;     for (int kt = 0; kt < nk; kt += 2) {
;       const bool last = kt + 2 >= nk;
;       G_WRITE(1, ra0, rb0);
;       if (!last) G_LOAD(Ag, Bg, kt + 2, ra0, rb0); else if (has_next) G_LOAD(Agn, Bgn, 0, ra0, rb0);
;       G_COMPUTE(0);
;       __syncthreads();
;       if (!last || has_next) G_WRITE(0, ra0, rb0);
;       if (!last) G_LOAD(Ag, Bg, kt + 3, ra0, rb0); else if (has_next) G_LOAD(Agn, Bgn, 1, ra0, rb0);
;       G_COMPUTE(1);
;       __syncthreads();
.LBB0_522:
	s_add_i32 s40, s40, 2
	s_add_u32 s68, s68, 0x100
	s_addc_u32 s69, s69, 0
	s_and_b64 vcc, exec, s[70:71]
	v_add_u32_e32 v0, v227, v228
	ds_read_b128 v[204:207], v0 offset:8192
	s_waitcnt lgkmcnt(1)
	v_mfma_f32_32x32x16_bf16 v[114:129], v[244:247], v[208:211], v[114:129]
	v_mfma_f32_32x32x16_bf16 v[82:97], v[244:247], v[232:235], v[82:97]
	ds_read_b128 v[244:247], v0 offset:12288
	v_add_u32_e32 v163, v226, v229
	ds_read_b128 v[236:239], v163
	ds_read_b128 v[240:243], v163 offset:4096
	v_mfma_f32_32x32x16_bf16 v[98:113], v[248:251], v[208:211], v[98:113]
	v_mfma_f32_32x32x16_bf16 v[66:81], v[248:251], v[232:235], v[66:81]
	v_add_u32_e32 v0, v227, v229
	ds_read_b128 v[248:251], v0 offset:0
	s_waitcnt lgkmcnt(4)
	v_mfma_f32_32x32x16_bf16 v[50:65], v[204:207], v[208:211], v[50:65]
	v_mfma_f32_32x32x16_bf16 v[18:33], v[204:207], v[232:235], v[18:33]
	ds_read_b128 v[204:207], v0 offset:4096
	s_waitcnt lgkmcnt(4)
	v_mfma_f32_32x32x16_bf16 v[34:49], v[244:247], v[208:211], v[34:49]
	v_mfma_f32_32x32x16_bf16 v[2:17], v[244:247], v[232:235], v[2:17]
	ds_read_b128 v[244:247], v0 offset:8192
	s_waitcnt lgkmcnt(2)
	v_mfma_f32_32x32x16_bf16 v[114:129], v[248:251], v[236:239], v[114:129]
	v_mfma_f32_32x32x16_bf16 v[82:97], v[248:251], v[240:243], v[82:97]
	ds_read_b128 v[248:251], v0 offset:12288
	v_add_u32_e32 v163, v226, v230
	ds_read_b128 v[208:211], v163
	ds_read_b128 v[232:235], v163 offset:4096
	s_waitcnt lgkmcnt(4)
	v_mfma_f32_32x32x16_bf16 v[98:113], v[204:207], v[236:239], v[98:113]
	v_mfma_f32_32x32x16_bf16 v[66:81], v[204:207], v[240:243], v[66:81]
	v_add_u32_e32 v0, v227, v230
	ds_read_b128 v[204:207], v0 offset:0
	s_waitcnt lgkmcnt(4)
	v_mfma_f32_32x32x16_bf16 v[50:65], v[244:247], v[236:239], v[50:65]
	v_mfma_f32_32x32x16_bf16 v[18:33], v[244:247], v[240:243], v[18:33]
	ds_read_b128 v[244:247], v0 offset:4096
	s_waitcnt lgkmcnt(4)
	v_mfma_f32_32x32x16_bf16 v[34:49], v[248:251], v[236:239], v[34:49]
	v_mfma_f32_32x32x16_bf16 v[2:17], v[248:251], v[240:243], v[2:17]
	ds_read_b128 v[248:251], v0 offset:8192
	s_waitcnt lgkmcnt(2)
	v_mfma_f32_32x32x16_bf16 v[114:129], v[204:207], v[208:211], v[114:129]
	v_mfma_f32_32x32x16_bf16 v[82:97], v[204:207], v[232:235], v[82:97]
	ds_read_b128 v[204:207], v0 offset:12288
	v_add_u32_e32 v163, v226, v231
	ds_read_b128 v[236:239], v163
	ds_read_b128 v[240:243], v163 offset:4096
	s_waitcnt lgkmcnt(4)
	v_mfma_f32_32x32x16_bf16 v[98:113], v[244:247], v[208:211], v[98:113]
	v_mfma_f32_32x32x16_bf16 v[66:81], v[244:247], v[232:235], v[66:81]
	v_add_u32_e32 v0, v227, v231
	ds_read_b128 v[244:247], v0 offset:0
	s_waitcnt lgkmcnt(4)
	v_mfma_f32_32x32x16_bf16 v[50:65], v[248:251], v[208:211], v[50:65]
	v_mfma_f32_32x32x16_bf16 v[18:33], v[248:251], v[232:235], v[18:33]
	ds_read_b128 v[248:251], v0 offset:4096
	s_waitcnt lgkmcnt(4)
	v_mfma_f32_32x32x16_bf16 v[34:49], v[204:207], v[208:211], v[34:49]
	v_mfma_f32_32x32x16_bf16 v[2:17], v[204:207], v[232:235], v[2:17]
	ds_read_b128 v[204:207], v0 offset:8192
	s_waitcnt lgkmcnt(2)
	v_mfma_f32_32x32x16_bf16 v[114:129], v[244:247], v[236:239], v[114:129]
	v_mfma_f32_32x32x16_bf16 v[82:97], v[244:247], v[240:243], v[82:97]
	ds_read_b128 v[244:247], v0 offset:12288
	s_waitcnt lgkmcnt(2)
	v_mfma_f32_32x32x16_bf16 v[98:113], v[248:251], v[236:239], v[98:113]
	v_mfma_f32_32x32x16_bf16 v[66:81], v[248:251], v[240:243], v[66:81]
	s_waitcnt lgkmcnt(0)
	s_barrier
	v_add_u32_e32 v163, v224, v228
	ds_read_b128 v[208:211], v163
	ds_read_b128 v[232:235], v163 offset:4096
	v_add_u32_e32 v0, v225, v228
	ds_read_b128 v[248:251], v0 offset:36864
	v_mfma_f32_32x32x16_bf16 v[50:65], v[204:207], v[236:239], v[50:65]
	v_mfma_f32_32x32x16_bf16 v[18:33], v[204:207], v[240:243], v[18:33]
	v_mfma_f32_32x32x16_bf16 v[34:49], v[244:247], v[236:239], v[34:49]
	v_mfma_f32_32x32x16_bf16 v[2:17], v[244:247], v[240:243], v[2:17]
	ds_read_b128 v[244:247], v0 offset:32768
	s_cbranch_vccnz .LBB0_537

; #define G_LOAD(AG, BG, kt, RA, RB) do { const int k0_ = (kt) * 64; int ac_ = k0_; if (g.remap) ac_ = k0_ < 512 ? k0_ : (k0_ < 1024 ? g.seg2 + k0_ - 512 : 2304 + k0_ - 1024); \
;     _Pragma("unroll") for (int i = 0; i < 4; ++i) { RA[i] = *(const u32x4*)(AG + (size_t)(64 * i) * g.lda + ac_); RB[i] = *(const u32x4*)(BG + (size_t)(64 * i) * g.K + k0_); } } while (0)
; #define G_WRITE(buf, RA, RB) do { _Pragma("unroll") for (int i = 0; i < 4; ++i) { *(u32x4*)(lds + (buf) * 65536 + i * 8192 + soff) = RA[i]; *(u32x4*)(lds + (buf) * 65536 + 32768 + i * 8192 + soff) = RB[i]; } } while (0)
; template <int EPI>
; DI void gemm_phase(char* lds, const Params& p, const GemmDesc g, int layer) {
;     ...
;     for (int kt = 0; kt < nk; kt += 2) {
;       const bool last = kt + 2 >= nk;
;       G_WRITE(1, ra0, rb0);
;       if (!last) G_LOAD(Ag, Bg, kt + 2, ra0, rb0); else if (has_next) G_LOAD(Agn, Bgn, 0, ra0, rb0);
;       G_COMPUTE(0);
;       __syncthreads();
;       if (!last || has_next) G_WRITE(0, ra0, rb0);
;       if (!last) G_LOAD(Ag, Bg, kt + 3, ra0, rb0); else if (has_next) G_LOAD(Agn, Bgn, 1, ra0, rb0);
;       G_COMPUTE(1);
;       __syncthreads();
.LBB0_529:
	s_or_b64 s[42:43], s[16:17], s[72:73]
	s_andn2_b64 vcc, exec, s[42:43]
	v_add_u32_e32 v0, v225, v228
	ds_read_b128 v[204:207], v0 offset:40960
	s_waitcnt lgkmcnt(1)
	v_mfma_f32_32x32x16_bf16 v[114:129], v[244:247], v[208:211], v[114:129]
	v_mfma_f32_32x32x16_bf16 v[82:97], v[244:247], v[232:235], v[82:97]
	ds_read_b128 v[244:247], v0 offset:45056
	v_add_u32_e32 v163, v224, v229
	ds_read_b128 v[236:239], v163
	ds_read_b128 v[240:243], v163 offset:4096
	v_mfma_f32_32x32x16_bf16 v[98:113], v[248:251], v[208:211], v[98:113]
	v_mfma_f32_32x32x16_bf16 v[66:81], v[248:251], v[232:235], v[66:81]
	v_add_u32_e32 v0, v225, v229
	ds_read_b128 v[248:251], v0 offset:32768
	s_waitcnt lgkmcnt(4)
	v_mfma_f32_32x32x16_bf16 v[50:65], v[204:207], v[208:211], v[50:65]
	v_mfma_f32_32x32x16_bf16 v[18:33], v[204:207], v[232:235], v[18:33]
	ds_read_b128 v[204:207], v0 offset:36864
	s_waitcnt lgkmcnt(4)
	v_mfma_f32_32x32x16_bf16 v[34:49], v[244:247], v[208:211], v[34:49]
	v_mfma_f32_32x32x16_bf16 v[2:17], v[244:247], v[232:235], v[2:17]
	ds_read_b128 v[244:247], v0 offset:40960
	s_waitcnt lgkmcnt(2)
	v_mfma_f32_32x32x16_bf16 v[114:129], v[248:251], v[236:239], v[114:129]
	v_mfma_f32_32x32x16_bf16 v[82:97], v[248:251], v[240:243], v[82:97]
	ds_read_b128 v[248:251], v0 offset:45056
	v_add_u32_e32 v163, v224, v230
	ds_read_b128 v[208:211], v163
	ds_read_b128 v[232:235], v163 offset:4096
	s_waitcnt lgkmcnt(4)
	v_mfma_f32_32x32x16_bf16 v[98:113], v[204:207], v[236:239], v[98:113]
	v_mfma_f32_32x32x16_bf16 v[66:81], v[204:207], v[240:243], v[66:81]
	v_add_u32_e32 v0, v225, v230
	ds_read_b128 v[204:207], v0 offset:32768
	s_waitcnt lgkmcnt(4)
	v_mfma_f32_32x32x16_bf16 v[50:65], v[244:247], v[236:239], v[50:65]
	v_mfma_f32_32x32x16_bf16 v[18:33], v[244:247], v[240:243], v[18:33]
	ds_read_b128 v[244:247], v0 offset:36864
	s_waitcnt lgkmcnt(4)
	v_mfma_f32_32x32x16_bf16 v[34:49], v[248:251], v[236:239], v[34:49]
	v_mfma_f32_32x32x16_bf16 v[2:17], v[248:251], v[240:243], v[2:17]
	ds_read_b128 v[248:251], v0 offset:40960
	s_waitcnt lgkmcnt(2)
	v_mfma_f32_32x32x16_bf16 v[114:129], v[204:207], v[208:211], v[114:129]
	v_mfma_f32_32x32x16_bf16 v[82:97], v[204:207], v[232:235], v[82:97]
	ds_read_b128 v[204:207], v0 offset:45056
	v_add_u32_e32 v163, v224, v231
	ds_read_b128 v[236:239], v163
	ds_read_b128 v[240:243], v163 offset:4096
	s_waitcnt lgkmcnt(4)
	v_mfma_f32_32x32x16_bf16 v[98:113], v[244:247], v[208:211], v[98:113]
	v_mfma_f32_32x32x16_bf16 v[66:81], v[244:247], v[232:235], v[66:81]
	v_add_u32_e32 v0, v225, v231
	ds_read_b128 v[244:247], v0 offset:32768
	s_waitcnt lgkmcnt(4)
	v_mfma_f32_32x32x16_bf16 v[50:65], v[248:251], v[208:211], v[50:65]
	v_mfma_f32_32x32x16_bf16 v[18:33], v[248:251], v[232:235], v[18:33]
	ds_read_b128 v[248:251], v0 offset:36864
	s_waitcnt lgkmcnt(4)
	v_mfma_f32_32x32x16_bf16 v[34:49], v[204:207], v[208:211], v[34:49]
	v_mfma_f32_32x32x16_bf16 v[2:17], v[204:207], v[232:235], v[2:17]
	ds_read_b128 v[204:207], v0 offset:40960
	s_waitcnt lgkmcnt(2)
	v_mfma_f32_32x32x16_bf16 v[114:129], v[244:247], v[236:239], v[114:129]
	v_mfma_f32_32x32x16_bf16 v[82:97], v[244:247], v[240:243], v[82:97]
	ds_read_b128 v[244:247], v0 offset:45056
	s_waitcnt lgkmcnt(2)
	v_mfma_f32_32x32x16_bf16 v[98:113], v[248:251], v[236:239], v[98:113]
	v_mfma_f32_32x32x16_bf16 v[66:81], v[248:251], v[240:243], v[66:81]
	s_waitcnt lgkmcnt(0)
	s_barrier
	v_add_u32_e32 v163, v226, v228
	ds_read_b128 v[208:211], v163
	ds_read_b128 v[232:235], v163 offset:4096
	v_add_u32_e32 v0, v227, v228
	ds_read_b128 v[248:251], v0 offset:4096
	v_mfma_f32_32x32x16_bf16 v[50:65], v[204:207], v[236:239], v[50:65]
	v_mfma_f32_32x32x16_bf16 v[18:33], v[204:207], v[240:243], v[18:33]
	v_mfma_f32_32x32x16_bf16 v[34:49], v[244:247], v[236:239], v[34:49]
	v_mfma_f32_32x32x16_bf16 v[2:17], v[244:247], v[240:243], v[2:17]
	ds_read_b128 v[244:247], v0 offset:0
	s_cbranch_vccnz .LBB0_532
	s_waitcnt vmcnt(7)
	ds_write_b128 v223, v[130:133]
	s_waitcnt vmcnt(6)
	ds_write_b128 v223, v[134:137] offset:32768
	s_waitcnt vmcnt(5)
	ds_write_b128 v223, v[138:141] offset:8192
	s_waitcnt vmcnt(4)
	ds_write_b128 v223, v[142:145] offset:40960
	s_waitcnt vmcnt(3)
	ds_write_b128 v223, v[146:149] offset:16384
	s_waitcnt vmcnt(2)
	ds_write_b128 v223, v[150:153] offset:49152
	s_waitcnt vmcnt(1)
	ds_write_b128 v223, v[154:157] offset:24576
	s_waitcnt vmcnt(0)
	ds_write_b128 v223, v[158:161] offset:57344
	s_mov_b64 s[72:73], -1
	s_and_b64 vcc, exec, s[70:71]
	s_cbranch_vccnz .LBB0_533
